# A loop edges: row-sum chain ahead of the loop-back barrier; K and V^T fragment reads lead the iteration, global prefetch after them
# baseline (speedup 1.0000x reference)
; #define LAS __attribute__((address_space(3)))
; template <int DQK, int NSUB, int MODE>
; __device__ __forceinline__ void flash_unit(LAS char* L, const bf16_t* Qp, int qpitch, const bf16_t* Kp, int kpitch, const bf16_t* Vp, int vpitch,
;                                            bf16_t* Op, int opitch, float lam, float oscale, const float* subln) {
;     ...
;     for (int t = 0; t < SEQ / 64; ++t) {
;         const int buf = t & 1;
;         if (t + 1 < SEQ / 64) { const size_t ko = (size_t)(t + 1) * 64 * kpitch, vo = (size_t)(t + 1) * 64 * vpitch;
;             rk1 = *(const u32x4*)(kg1 + ko); if (has2) rk2 = *(const u32x4*)(kg2 + ko); rv1 = *(const u32x4*)(vg1 + vo); }
;         const char* Kb = Lg + buf * KBUF; LAS const char* Vb = L + OFF_V + buf * VBUF + voff;
; #pragma unroll
;         for (int s = 0; s < NSUB; ++s) {
;             f32x16 p0, p1;
; #pragma unroll
;             for (int d0 = 0; d0 < ND0; ++d0) { const bf16x8 k0 = *(const bf16x8*)(Kb + r32 * KPB + (s * DQK + 16 * d0 + 8 * hi) * 2); const bf16x8 k1 = *(const bf16x8*)(Kb + (32 + r32) * KPB + (s * DQK + 16 * d0 + 8 * hi) * 2);
;     ...
;                   for (int r = 2; r < 16; r += 2) r2 += (f32x2_){ph[r], ph[r + 1]};
;                   lrow[s] += r2[0] + r2[1]; }
;     ...
;         __syncthreads();
.LBB0_574:
	v_pk_add_f32 v[96:97], v[96:97], v[98:99]
	s_add_u32 s10, s10, 0x50000
	v_pk_add_f32 v[96:97], v[100:101], v[96:97]
	s_addc_u32 s11, s11, 0
	v_pk_add_f32 v[96:97], v[102:103], v[96:97]
	s_add_i32 s22, s22, 1
	v_pk_add_f32 v[96:97], v[104:105], v[96:97]
	s_cmp_lg_u32 s10, 0x9b0000
	v_pk_add_f32 v[96:97], v[106:107], v[96:97]
	s_nop 0
	v_pk_add_f32 v[96:97], v[108:109], v[96:97]
	s_nop 0
	v_pk_add_f32 v[96:97], v[110:111], v[96:97]
	s_nop 0
	v_add_f32_e32 v96, v96, v97
	v_add_f32_e32 v160, v112, v96
	v_pk_add_f32 v[96:97], v[168:169], v[170:171]
	s_nop 0
	v_pk_add_f32 v[96:97], v[172:173], v[96:97]
	s_nop 0
	v_pk_add_f32 v[96:97], v[174:175], v[96:97]
	s_nop 0
	v_pk_add_f32 v[96:97], v[176:177], v[96:97]
	s_nop 0
	v_pk_add_f32 v[96:97], v[178:179], v[96:97]
	s_nop 0
	v_pk_add_f32 v[96:97], v[180:181], v[96:97]
	s_nop 0
	v_pk_add_f32 v[96:97], v[182:183], v[96:97]
	s_nop 0
	v_add_f32_e32 v96, v96, v97
	v_add_f32_e32 v168, v194, v96
	s_waitcnt lgkmcnt(0)
	s_barrier
	s_cbranch_scc0 .LBB0_555
.LBB0_575:
	s_and_b32 s98, s22, 1
	s_mul_i32 s98, s98, 0x2400
	v_add_u32_e32 v195, s98, v192
	v_add_u32_e32 v229, s98, v191
	ds_read_b128 v[96:99], v195
	ds_read_b128 v[100:103], v195 offset:32
	ds_read_b128 v[170:173], v195 offset:4608
	ds_read_b128 v[174:177], v195 offset:4640
	ds_read_b64_tr_b16 v[204:205], v229 offset:18432
	ds_read_b64_tr_b16 v[206:207], v229 offset:19584
	ds_read_b64_tr_b16 v[208:209], v229 offset:20736
	ds_read_b64_tr_b16 v[210:211], v229 offset:21888
	ds_read_b64_tr_b16 v[212:213], v229 offset:18496
	ds_read_b64_tr_b16 v[214:215], v229 offset:19648
	ds_read_b64_tr_b16 v[216:217], v229 offset:20800
	ds_read_b64_tr_b16 v[218:219], v229 offset:21952
	s_cmp_lg_u32 s10, 0x960000
	s_cselect_b64 s[14:15], -1, 0
	s_cmp_eq_u32 s10, 0x960000
	s_cbranch_scc1 .LBB0_579
	v_lshl_add_u64 v[248:249], v[166:167], 0, s[10:11]
	s_waitcnt vmcnt(0)
	global_load_dwordx4 v[148:151], v[248:249], off
	s_and_saveexec_b64 s[8:9], s[36:37]
	s_cbranch_execz .LBB0_578
	v_lshl_add_u64 v[248:249], v[164:165], 0, s[10:11]
	global_load_dwordx4 v[144:147], v[248:249], off
.LBB0_578:
	s_or_b64 exec, exec, s[8:9]
	v_lshl_add_u64 v[248:249], v[162:163], 0, s[10:11]
	global_load_dwordx4 v[152:155], v[248:249], off
.LBB0_579:
	s_and_b32 s8, s22, 1
	s_mul_i32 s9, s8, 0x2400
	s_waitcnt lgkmcnt(8)
	v_mfma_f32_32x32x16_bf16 v[112:127], v[96:99], v[128:131], v[32:47]
	v_mfma_f32_32x32x16_bf16 v[112:127], v[100:103], v[132:135], v[112:127]
	s_nop 11
	v_max_f32_e32 v158, v113, v113
	v_max_f32_e32 v169, v112, v112
	v_mfma_f32_32x32x16_bf16 v[96:111], v[170:173], v[128:131], v[32:47]
	v_max_f32_e32 v158, v169, v158
	v_max3_f32 v158, v158, v114, v115
	v_max3_f32 v158, v158, v116, v117
	v_max3_f32 v158, v158, v118, v119
	v_max3_f32 v158, v158, v120, v121
	v_max3_f32 v158, v158, v122, v123
	v_max3_f32 v158, v158, v124, v125
	v_max3_f32 v158, v158, v126, v127
	v_mfma_f32_32x32x16_bf16 v[96:111], v[174:177], v[132:135], v[96:111]
	v_cmp_lt_f32_e32 vcc, s61, v158
	s_cbranch_vccz .LBB0_581
	ds_bpermute_b32 v169, v184, v158
	s_waitcnt lgkmcnt(0)
	v_max_f32_e32 v169, v169, v169
	v_max_f32_e32 v158, v158, v169
	v_max_f32_e32 v32, v158, v158
	v_max_f32_e32 v34, 0, v32
	v_exp_f32_e64 v36, -v34
	v_add_f32_e32 v159, v159, v34
	v_xor_b32_e32 v32, 0x80000000, v159
	v_pk_add_f32 v[112:113], v[112:113], v[34:35] op_sel_hi:[1,0] neg_lo:[0,1] neg_hi:[0,1]
	v_pk_add_f32 v[114:115], v[114:115], v[34:35] op_sel_hi:[1,0] neg_lo:[0,1] neg_hi:[0,1]
	v_pk_add_f32 v[116:117], v[116:117], v[34:35] op_sel_hi:[1,0] neg_lo:[0,1] neg_hi:[0,1]
	v_pk_add_f32 v[118:119], v[118:119], v[34:35] op_sel_hi:[1,0] neg_lo:[0,1] neg_hi:[0,1]
	v_pk_add_f32 v[120:121], v[120:121], v[34:35] op_sel_hi:[1,0] neg_lo:[0,1] neg_hi:[0,1]
	v_pk_add_f32 v[122:123], v[122:123], v[34:35] op_sel_hi:[1,0] neg_lo:[0,1] neg_hi:[0,1]
	v_pk_add_f32 v[124:125], v[124:125], v[34:35] op_sel_hi:[1,0] neg_lo:[0,1] neg_hi:[0,1]
	v_pk_add_f32 v[126:127], v[126:127], v[34:35] op_sel_hi:[1,0] neg_lo:[0,1] neg_hi:[0,1]
	v_sub_f32_e32 v111, v111, v34
	v_sub_f32_e32 v110, v110, v34
	v_sub_f32_e32 v109, v109, v34
	v_sub_f32_e32 v108, v108, v34
	v_sub_f32_e32 v107, v107, v34
	v_sub_f32_e32 v106, v106, v34
	v_sub_f32_e32 v105, v105, v34
	v_sub_f32_e32 v104, v104, v34
	v_sub_f32_e32 v103, v103, v34
	v_sub_f32_e32 v102, v102, v34
	v_sub_f32_e32 v101, v101, v34
	v_sub_f32_e32 v100, v100, v34
	v_sub_f32_e32 v99, v99, v34
	v_sub_f32_e32 v98, v98, v34
	v_sub_f32_e32 v97, v97, v34
	v_sub_f32_e32 v96, v96, v34
	v_pk_mul_f32 v[14:15], v[14:15], v[36:37] op_sel_hi:[1,0]
	v_pk_mul_f32 v[12:13], v[12:13], v[36:37] op_sel_hi:[1,0]
	v_pk_mul_f32 v[10:11], v[10:11], v[36:37] op_sel_hi:[1,0]
	v_pk_mul_f32 v[8:9], v[8:9], v[36:37] op_sel_hi:[1,0]
	v_pk_mul_f32 v[6:7], v[6:7], v[36:37] op_sel_hi:[1,0]
	v_pk_mul_f32 v[4:5], v[4:5], v[36:37] op_sel_hi:[1,0]
	v_pk_mul_f32 v[2:3], v[2:3], v[36:37] op_sel_hi:[1,0]
	v_pk_mul_f32 v[0:1], v[0:1], v[36:37] op_sel_hi:[1,0]
	v_pk_mul_f32 v[30:31], v[30:31], v[36:37] op_sel_hi:[1,0]
	v_pk_mul_f32 v[28:29], v[28:29], v[36:37] op_sel_hi:[1,0]
	v_pk_mul_f32 v[26:27], v[26:27], v[36:37] op_sel_hi:[1,0]
	v_pk_mul_f32 v[24:25], v[24:25], v[36:37] op_sel_hi:[1,0]
	v_pk_mul_f32 v[22:23], v[22:23], v[36:37] op_sel_hi:[1,0]
	v_pk_mul_f32 v[20:21], v[20:21], v[36:37] op_sel_hi:[1,0]
	v_pk_mul_f32 v[18:19], v[18:19], v[36:37] op_sel_hi:[1,0]
	v_pk_mul_f32 v[16:17], v[16:17], v[36:37] op_sel_hi:[1,0]
	v_mul_f32_e32 v168, v168, v36
	v_mov_b32_e32 v33, v32
	v_mov_b32_e32 v34, v32
	v_mov_b32_e32 v35, v32
	v_mov_b32_e32 v36, v32
	v_mov_b32_e32 v37, v32
	v_mov_b32_e32 v38, v32
	v_mov_b32_e32 v39, v32
	v_mov_b32_e32 v40, v32
	v_mov_b32_e32 v41, v32
	v_mov_b32_e32 v42, v32
	v_mov_b32_e32 v43, v32
	v_mov_b32_e32 v44, v32
	v_mov_b32_e32 v45, v32
	v_mov_b32_e32 v46, v32
	v_mov_b32_e32 v47, v32
